# Fourier stage-1 epilogue: twiddle reads issued together, adjacent lanes paired via DPP so each lane stores one dword (half the store instructions)
# speedup vs baseline: 1.0033x; 1.0033x over previous
.LBB0_750:
	s_and_saveexec_b64 s[40:41], s[0:1]
	s_cbranch_execz .Lfft1_skip
	v_add_u32_e32 v30, s43, v111
	ds_read_b64_tr_b16 v[2:3], v30 offset:0
	ds_read_b64_tr_b16 v[4:5], v30 offset:0x800
	ds_read_b64_tr_b16 v[18:19], v30 offset:0x1000
	ds_read_b64_tr_b16 v[20:21], v30 offset:0x1800
	ds_read_b64_tr_b16 v[22:23], v30 offset:0x2000
	ds_read_b64_tr_b16 v[24:25], v30 offset:0x2800
	ds_read_b64_tr_b16 v[26:27], v30 offset:0x3000
	ds_read_b64_tr_b16 v[28:29], v30 offset:0x3800
	s_waitcnt lgkmcnt(0)
	s_nop 0
	v_mfma_f32_32x32x16_bf16 v[2:17], v[46:49], v[2:5], 0
	v_mfma_f32_32x32x16_bf16 v[2:17], v[42:45], v[18:21], v[2:17]
	ds_read_b64_tr_b16 v[18:19], v30 offset:0x200
	ds_read_b64_tr_b16 v[20:21], v30 offset:0xa00
	ds_read_b64_tr_b16 v[114:115], v30 offset:0x1200
	ds_read_b64_tr_b16 v[116:117], v30 offset:0x1a00
	ds_read_b64_tr_b16 v[118:119], v30 offset:0x2200
	ds_read_b64_tr_b16 v[120:121], v30 offset:0x2a00
	ds_read_b64_tr_b16 v[122:123], v30 offset:0x3200
	v_mfma_f32_32x32x16_bf16 v[2:17], v[38:41], v[22:25], v[2:17]
	ds_read_b64_tr_b16 v[124:125], v30 offset:0x3a00
	s_waitcnt lgkmcnt(0)
	v_mfma_f32_32x32x16_bf16 v[2:17], v[34:37], v[26:29], v[2:17]
	v_mfma_f32_32x32x16_bf16 v[18:33], v[46:49], v[18:21], 0
	s_ashr_i32 s44, s42, 9
	s_ashr_i32 s45, s44, 31
	s_and_b32 s36, s48, 0x380
	s_bfe_u32 s60, s42, 0x60003
	s_lshl_b64 s[42:43], s[44:45], 13
	s_lshl_b32 s36, s36, 1
	s_or_b32 s42, s42, s60
	v_mfma_f32_32x32x16_bf16 v[18:33], v[42:45], v[114:117], v[18:33]
	v_lshl_add_u64 v[104:105], v[78:79], 0, s[36:37]
	v_mfma_f32_32x32x16_bf16 v[18:33], v[38:41], v[118:121], v[18:33]
	v_mfma_f32_32x32x16_bf16 v[18:33], v[34:37], v[122:125], v[18:33]
	s_waitcnt vmcnt(0)
	v_pk_add_f32 v[100:101], v[132:133], 1.0 op_sel_hi:[1,0]
	v_pk_add_f32 v[96:97], v[128:129], 1.0 op_sel_hi:[1,0]
	v_pk_add_f32 v[98:99], v[126:127], 1.0 op_sel_hi:[1,0]
	v_pk_add_f32 v[102:103], v[130:131], 1.0 op_sel_hi:[1,0]
	s_mov_b64 s[44:45], exec
	v_mul_u32_u24_e32 v150, s60, v89
	v_lshl_add_u32 v150, v150, 2, 0
	v_add_u32_e32 v150, 0x10000, v150
	ds_read2st64_b32 v[134:135], v150 offset1:16
	v_mul_u32_u24_e32 v150, s60, v93
	v_lshl_add_u32 v150, v150, 2, 0
	v_add_u32_e32 v150, 0x10000, v150
	ds_read2st64_b32 v[136:137], v150 offset1:16
	v_mul_u32_u24_e32 v150, s60, v95
	v_lshl_add_u32 v150, v150, 2, 0
	v_add_u32_e32 v150, 0x10000, v150
	ds_read2st64_b32 v[138:139], v150 offset1:16
	v_mul_u32_u24_e32 v150, s60, v106
	v_lshl_add_u32 v150, v150, 2, 0
	v_add_u32_e32 v150, 0x10000, v150
	ds_read2st64_b32 v[140:141], v150 offset1:16
	v_mul_u32_u24_e32 v150, s60, v107
	v_lshl_add_u32 v150, v150, 2, 0
	v_add_u32_e32 v150, 0x10000, v150
	ds_read2st64_b32 v[142:143], v150 offset1:16
	v_mul_u32_u24_e32 v150, s60, v108
	v_lshl_add_u32 v150, v150, 2, 0
	v_add_u32_e32 v150, 0x10000, v150
	ds_read2st64_b32 v[144:145], v150 offset1:16
	v_mul_u32_u24_e32 v150, s60, v109
	v_lshl_add_u32 v150, v150, 2, 0
	v_add_u32_e32 v150, 0x10000, v150
	ds_read2st64_b32 v[146:147], v150 offset1:16
	v_mul_u32_u24_e32 v150, s60, v110
	v_lshl_add_u32 v150, v150, 2, 0
	v_add_u32_e32 v150, 0x10000, v150
	ds_read2st64_b32 v[148:149], v150 offset1:16
	v_mbcnt_lo_u32_b32 v152, -1, 0
	v_mbcnt_hi_u32_b32 v152, -1, v152
	v_and_b32_e32 v152, 1, v152
	v_mul_u32_u24_e32 v152, 62, v152
	v_mov_b32_e32 v153, 0
	v_lshl_add_u64 v[154:155], v[104:105], 0, v[152:153]
	v_add_co_u32_e32 v156, vcc, 0x20000, v154
	s_nop 1
	v_addc_co_u32_e32 v157, vcc, 0, v155, vcc
	s_mov_b32 vcc_lo, 0xaaaaaaaa
	s_mov_b32 vcc_hi, 0xaaaaaaaa
	s_waitcnt lgkmcnt(7)
	v_mul_f32_e32 v158, v10, v135
	v_mul_f32_e32 v159, v26, v135
	v_mul_f32_e32 v160, v10, v134
	v_mul_f32_e32 v161, v26, v134
	v_fma_f32 v158, v2, v134, -v158
	v_fma_f32 v159, v18, v134, -v159
	v_fmac_f32_e32 v160, v2, v135
	v_fmac_f32_e32 v161, v18, v135
	v_or_b32_e32 v162, s42, v80
	v_mov_b32_e32 v163, s43
	v_lshlrev_b64 v[162:163], 11, v[162:163]
	v_mov_b32_dpp v164, v158 quad_perm:[1,0,3,2] row_mask:0xf bank_mask:0xf
	v_mov_b32_dpp v165, v159 quad_perm:[1,0,3,2] row_mask:0xf bank_mask:0xf
	v_mov_b32_dpp v166, v160 quad_perm:[1,0,3,2] row_mask:0xf bank_mask:0xf
	v_mov_b32_dpp v167, v161 quad_perm:[1,0,3,2] row_mask:0xf bank_mask:0xf
	v_lshl_add_u64 v[168:169], v[154:155], 0, v[162:163]
	v_lshl_add_u64 v[170:171], v[156:157], 0, v[162:163]
	v_cvt_pk_bf16_f32 v172, v158, v164
	v_cvt_pk_bf16_f32 v173, v165, v159
	v_cndmask_b32_e32 v172, v172, v173, vcc
	v_cvt_pk_bf16_f32 v174, v160, v166
	v_cvt_pk_bf16_f32 v175, v167, v161
	v_cndmask_b32_e32 v174, v174, v175, vcc
	s_and_b64 exec, s[44:45], s[4:5]
	global_store_dword v[168:169], v172, off
	global_store_dword v[170:171], v174, off
	s_mov_b64 exec, s[44:45]
	s_waitcnt lgkmcnt(6)
	v_mul_f32_e32 v158, v11, v137
	v_mul_f32_e32 v159, v27, v137
	v_mul_f32_e32 v160, v11, v136
	v_mul_f32_e32 v161, v27, v136
	v_fma_f32 v158, v3, v136, -v158
	v_fma_f32 v159, v19, v136, -v159
	v_fmac_f32_e32 v160, v3, v137
	v_fmac_f32_e32 v161, v19, v137
	v_or_b32_e32 v162, s42, v82
	v_mov_b32_e32 v163, s43
	v_lshlrev_b64 v[162:163], 11, v[162:163]
	v_mov_b32_dpp v164, v158 quad_perm:[1,0,3,2] row_mask:0xf bank_mask:0xf
	v_mov_b32_dpp v165, v159 quad_perm:[1,0,3,2] row_mask:0xf bank_mask:0xf
	v_mov_b32_dpp v166, v160 quad_perm:[1,0,3,2] row_mask:0xf bank_mask:0xf
	v_mov_b32_dpp v167, v161 quad_perm:[1,0,3,2] row_mask:0xf bank_mask:0xf
	v_lshl_add_u64 v[168:169], v[154:155], 0, v[162:163]
	v_lshl_add_u64 v[170:171], v[156:157], 0, v[162:163]
	v_cvt_pk_bf16_f32 v172, v158, v164
	v_cvt_pk_bf16_f32 v173, v165, v159
	v_cndmask_b32_e32 v172, v172, v173, vcc
	v_cvt_pk_bf16_f32 v174, v160, v166
	v_cvt_pk_bf16_f32 v175, v167, v161
	v_cndmask_b32_e32 v174, v174, v175, vcc
	s_and_b64 exec, s[44:45], s[6:7]
	global_store_dword v[168:169], v172, off
	global_store_dword v[170:171], v174, off
	s_mov_b64 exec, s[44:45]
	s_waitcnt lgkmcnt(5)
	v_mul_f32_e32 v158, v12, v139
	v_mul_f32_e32 v159, v28, v139
	v_mul_f32_e32 v160, v12, v138
	v_mul_f32_e32 v161, v28, v138
	v_fma_f32 v158, v4, v138, -v158
	v_fma_f32 v159, v20, v138, -v159
	v_fmac_f32_e32 v160, v4, v139
	v_fmac_f32_e32 v161, v20, v139
	v_or_b32_e32 v162, s42, v84
	v_mov_b32_e32 v163, s43
	v_lshlrev_b64 v[162:163], 11, v[162:163]
	v_mov_b32_dpp v164, v158 quad_perm:[1,0,3,2] row_mask:0xf bank_mask:0xf
	v_mov_b32_dpp v165, v159 quad_perm:[1,0,3,2] row_mask:0xf bank_mask:0xf
	v_mov_b32_dpp v166, v160 quad_perm:[1,0,3,2] row_mask:0xf bank_mask:0xf
	v_mov_b32_dpp v167, v161 quad_perm:[1,0,3,2] row_mask:0xf bank_mask:0xf
	v_lshl_add_u64 v[168:169], v[154:155], 0, v[162:163]
	v_lshl_add_u64 v[170:171], v[156:157], 0, v[162:163]
	v_cvt_pk_bf16_f32 v172, v158, v164
	v_cvt_pk_bf16_f32 v173, v165, v159
	v_cndmask_b32_e32 v172, v172, v173, vcc
	v_cvt_pk_bf16_f32 v174, v160, v166
	v_cvt_pk_bf16_f32 v175, v167, v161
	v_cndmask_b32_e32 v174, v174, v175, vcc
	s_and_b64 exec, s[44:45], s[8:9]
	global_store_dword v[168:169], v172, off
	global_store_dword v[170:171], v174, off
	s_mov_b64 exec, s[44:45]
	s_waitcnt lgkmcnt(4)
	v_mul_f32_e32 v158, v13, v141
	v_mul_f32_e32 v159, v29, v141
	v_mul_f32_e32 v160, v13, v140
	v_mul_f32_e32 v161, v29, v140
	v_fma_f32 v158, v5, v140, -v158
	v_fma_f32 v159, v21, v140, -v159
	v_fmac_f32_e32 v160, v5, v141
	v_fmac_f32_e32 v161, v21, v141
	v_or_b32_e32 v162, s42, v86
	v_mov_b32_e32 v163, s43
	v_lshlrev_b64 v[162:163], 11, v[162:163]
	v_mov_b32_dpp v164, v158 quad_perm:[1,0,3,2] row_mask:0xf bank_mask:0xf
	v_mov_b32_dpp v165, v159 quad_perm:[1,0,3,2] row_mask:0xf bank_mask:0xf
	v_mov_b32_dpp v166, v160 quad_perm:[1,0,3,2] row_mask:0xf bank_mask:0xf
	v_mov_b32_dpp v167, v161 quad_perm:[1,0,3,2] row_mask:0xf bank_mask:0xf
	v_lshl_add_u64 v[168:169], v[154:155], 0, v[162:163]
	v_lshl_add_u64 v[170:171], v[156:157], 0, v[162:163]
	v_cvt_pk_bf16_f32 v172, v158, v164
	v_cvt_pk_bf16_f32 v173, v165, v159
	v_cndmask_b32_e32 v172, v172, v173, vcc
	v_cvt_pk_bf16_f32 v174, v160, v166
	v_cvt_pk_bf16_f32 v175, v167, v161
	v_cndmask_b32_e32 v174, v174, v175, vcc
	s_and_b64 exec, s[44:45], s[10:11]
	global_store_dword v[168:169], v172, off
	global_store_dword v[170:171], v174, off
	s_mov_b64 exec, s[44:45]
	s_waitcnt lgkmcnt(3)
	v_mul_f32_e32 v158, v14, v143
	v_mul_f32_e32 v159, v30, v143
	v_mul_f32_e32 v160, v14, v142
	v_mul_f32_e32 v161, v30, v142
	v_fma_f32 v158, v6, v142, -v158
	v_fma_f32 v159, v22, v142, -v159
	v_fmac_f32_e32 v160, v6, v143
	v_fmac_f32_e32 v161, v22, v143
	v_or_b32_e32 v162, s42, v88
	v_mov_b32_e32 v163, s43
	v_lshlrev_b64 v[162:163], 11, v[162:163]
	v_mov_b32_dpp v164, v158 quad_perm:[1,0,3,2] row_mask:0xf bank_mask:0xf
	v_mov_b32_dpp v165, v159 quad_perm:[1,0,3,2] row_mask:0xf bank_mask:0xf
	v_mov_b32_dpp v166, v160 quad_perm:[1,0,3,2] row_mask:0xf bank_mask:0xf
	v_mov_b32_dpp v167, v161 quad_perm:[1,0,3,2] row_mask:0xf bank_mask:0xf
	v_lshl_add_u64 v[168:169], v[154:155], 0, v[162:163]
	v_lshl_add_u64 v[170:171], v[156:157], 0, v[162:163]
	v_cvt_pk_bf16_f32 v172, v158, v164
	v_cvt_pk_bf16_f32 v173, v165, v159
	v_cndmask_b32_e32 v172, v172, v173, vcc
	v_cvt_pk_bf16_f32 v174, v160, v166
	v_cvt_pk_bf16_f32 v175, v167, v161
	v_cndmask_b32_e32 v174, v174, v175, vcc
	s_and_b64 exec, s[44:45], s[12:13]
	global_store_dword v[168:169], v172, off
	global_store_dword v[170:171], v174, off
	s_mov_b64 exec, s[44:45]
	s_waitcnt lgkmcnt(2)
	v_mul_f32_e32 v158, v15, v145
	v_mul_f32_e32 v159, v31, v145
	v_mul_f32_e32 v160, v15, v144
	v_mul_f32_e32 v161, v31, v144
	v_fma_f32 v158, v7, v144, -v158
	v_fma_f32 v159, v23, v144, -v159
	v_fmac_f32_e32 v160, v7, v145
	v_fmac_f32_e32 v161, v23, v145
	v_or_b32_e32 v162, s42, v90
	v_mov_b32_e32 v163, s43
	v_lshlrev_b64 v[162:163], 11, v[162:163]
	v_mov_b32_dpp v164, v158 quad_perm:[1,0,3,2] row_mask:0xf bank_mask:0xf
	v_mov_b32_dpp v165, v159 quad_perm:[1,0,3,2] row_mask:0xf bank_mask:0xf
	v_mov_b32_dpp v166, v160 quad_perm:[1,0,3,2] row_mask:0xf bank_mask:0xf
	v_mov_b32_dpp v167, v161 quad_perm:[1,0,3,2] row_mask:0xf bank_mask:0xf
	v_lshl_add_u64 v[168:169], v[154:155], 0, v[162:163]
	v_lshl_add_u64 v[170:171], v[156:157], 0, v[162:163]
	v_cvt_pk_bf16_f32 v172, v158, v164
	v_cvt_pk_bf16_f32 v173, v165, v159
	v_cndmask_b32_e32 v172, v172, v173, vcc
	v_cvt_pk_bf16_f32 v174, v160, v166
	v_cvt_pk_bf16_f32 v175, v167, v161
	v_cndmask_b32_e32 v174, v174, v175, vcc
	s_and_b64 exec, s[44:45], s[14:15]
	global_store_dword v[168:169], v172, off
	global_store_dword v[170:171], v174, off
	s_mov_b64 exec, s[44:45]
	s_waitcnt lgkmcnt(1)
	v_mul_f32_e32 v158, v16, v147
	v_mul_f32_e32 v159, v32, v147
	v_mul_f32_e32 v160, v16, v146
	v_mul_f32_e32 v161, v32, v146
	v_fma_f32 v158, v8, v146, -v158
	v_fma_f32 v159, v24, v146, -v159
	v_fmac_f32_e32 v160, v8, v147
	v_fmac_f32_e32 v161, v24, v147
	v_or_b32_e32 v162, s42, v92
	v_mov_b32_e32 v163, s43
	v_lshlrev_b64 v[162:163], 11, v[162:163]
	v_mov_b32_dpp v164, v158 quad_perm:[1,0,3,2] row_mask:0xf bank_mask:0xf
	v_mov_b32_dpp v165, v159 quad_perm:[1,0,3,2] row_mask:0xf bank_mask:0xf
	v_mov_b32_dpp v166, v160 quad_perm:[1,0,3,2] row_mask:0xf bank_mask:0xf
	v_mov_b32_dpp v167, v161 quad_perm:[1,0,3,2] row_mask:0xf bank_mask:0xf
	v_lshl_add_u64 v[168:169], v[154:155], 0, v[162:163]
	v_lshl_add_u64 v[170:171], v[156:157], 0, v[162:163]
	v_cvt_pk_bf16_f32 v172, v158, v164
	v_cvt_pk_bf16_f32 v173, v165, v159
	v_cndmask_b32_e32 v172, v172, v173, vcc
	v_cvt_pk_bf16_f32 v174, v160, v166
	v_cvt_pk_bf16_f32 v175, v167, v161
	v_cndmask_b32_e32 v174, v174, v175, vcc
	s_and_b64 exec, s[44:45], s[16:17]
	global_store_dword v[168:169], v172, off
	global_store_dword v[170:171], v174, off
	s_mov_b64 exec, s[44:45]
	s_waitcnt lgkmcnt(0)
	v_mul_f32_e32 v158, v17, v149
	v_mul_f32_e32 v159, v33, v149
	v_mul_f32_e32 v160, v17, v148
	v_mul_f32_e32 v161, v33, v148
	v_fma_f32 v158, v9, v148, -v158
	v_fma_f32 v159, v25, v148, -v159
	v_fmac_f32_e32 v160, v9, v149
	v_fmac_f32_e32 v161, v25, v149
	v_or_b32_e32 v162, s42, v94
	v_mov_b32_e32 v163, s43
	v_lshlrev_b64 v[162:163], 11, v[162:163]
	v_mov_b32_dpp v164, v158 quad_perm:[1,0,3,2] row_mask:0xf bank_mask:0xf
	v_mov_b32_dpp v165, v159 quad_perm:[1,0,3,2] row_mask:0xf bank_mask:0xf
	v_mov_b32_dpp v166, v160 quad_perm:[1,0,3,2] row_mask:0xf bank_mask:0xf
	v_mov_b32_dpp v167, v161 quad_perm:[1,0,3,2] row_mask:0xf bank_mask:0xf
	v_lshl_add_u64 v[168:169], v[154:155], 0, v[162:163]
	v_lshl_add_u64 v[170:171], v[156:157], 0, v[162:163]
	v_cvt_pk_bf16_f32 v172, v158, v164
	v_cvt_pk_bf16_f32 v173, v165, v159
	v_cndmask_b32_e32 v172, v172, v173, vcc
	v_cvt_pk_bf16_f32 v174, v160, v166
	v_cvt_pk_bf16_f32 v175, v167, v161
	v_cndmask_b32_e32 v174, v174, v175, vcc
	s_and_b64 exec, s[44:45], s[18:19]
	global_store_dword v[168:169], v172, off
	global_store_dword v[170:171], v174, off
	s_mov_b64 exec, s[44:45]
	s_branch .LBB0_747
